# token-MLP tile: A-fragment ds_reads pipelined 4 deep with counted lgkmcnt instead of read-wait-mfma; plus P5 sab-load batching
# baseline (speedup 1.0000x reference)
; #define LAS __attribute__((address_space(3)))
; __device__ __forceinline__ void mlp_tile(const Ctx& C, int l, int ct, int hd) {
;     ...
;         for (int sw = 0; sw < 4; ++sw) { const int s = sw * 32 + (tid >> 4);
;             vv[sw] = *(const u32x4*)(vn + (size_t)(T.row0 + min(s, T.nvalid - 1)) * GW + hd * 128 + d8); }
; #pragma unroll
;         for (int sw = 0; sw < 4; ++sw) { const int s = sw * 32 + (tid >> 4); if (s >= T.nvalid) vv[sw] = (u32x4){0u, 0u, 0u, 0u}; }
;         if (wact) {
;             const bf16_t* wp = (const bf16_t*)(C.ws + WS_WSP) + ((size_t)(l * 8 + hd) * 128 + t) * 128 + 8 * fq;
; #pragma unroll
;             for (int kk = 0; kk < 4; ++kk) wfr[kk] = *(const bf16x8*)(wp + 32 * kk);
; #pragma unroll
;             for (int n = 0; n < 8; ++n) uw[n] = *(const u32x2*)(proj + (size_t)row * NPROJ + 2048 + hd * 128 + 16 * n + 4 * fq);
;             bs = C.in[16][(size_t)(l * 8 + hd) * 128 + t];
;         }
; #pragma unroll
;         for (int sw = 0; sw < 4; ++sw) { const int s = sw * 32 + (tid >> 4); const u32x4 v = vv[sw];
;             const int sc = ((((s >> 3) ^ (tid & 15)) << 3) | (s & 7));
;             VT[(d8 + 0) * SX + sc] = (bf16_t)(v.x & 0xffffu); VT[(d8 + 1) * SX + sc] = (bf16_t)(v.x >> 16);
;             VT[(d8 + 2) * SX + sc] = (bf16_t)(v.y & 0xffffu); VT[(d8 + 3) * SX + sc] = (bf16_t)(v.y >> 16);
;             VT[(d8 + 4) * SX + sc] = (bf16_t)(v.z & 0xffffu); VT[(d8 + 5) * SX + sc] = (bf16_t)(v.z >> 16);
;             VT[(d8 + 6) * SX + sc] = (bf16_t)(v.w & 0xffffu); VT[(d8 + 7) * SX + sc] = (bf16_t)(v.w >> 16);
;         }
;     }
;     __syncthreads();
;     if (wact) {
;         const int nk = ((16 * w + 15) >> 5) + 1;
;         f32x4 acc[8];
; #pragma unroll
;         for (int n = 0; n < 8; ++n) acc[n] = (f32x4){0.f, 0.f, 0.f, 0.f};
; #pragma unroll
;         for (int kk = 0; kk < 4; ++kk) {
;             if (kk >= nk) break;
;             const bf16x8 wf = wfr[kk];
; #pragma unroll
;             for (int n = 0; n < 8; ++n) { const bf16x8 vf = *(const LAS bf16x8*)(VT + (16 * n + fr) * SX + (((4 * kk + fq) ^ (2 * n + (fr >> 3))) << 3));
;                 acc[n] = __builtin_amdgcn_mfma_f32_16x16x32_bf16(vf, wf, acc[n], 0, 0, 0); }
.LBB0_916:
	v_sub_u32_e32 v0, s2, v110
	v_cmp_lt_i32_e32 vcc, 0, v0
	s_movk_i32 s2, 0x60
	s_waitcnt vmcnt(3)
	v_cndmask_b32_e32 v9, 0, v9, vcc
	v_cndmask_b32_e32 v8, 0, v8, vcc
	v_cndmask_b32_e32 v7, 0, v7, vcc
	v_cndmask_b32_e32 v6, 0, v6, vcc
	v_cmp_lt_i32_e32 vcc, 32, v0
	s_waitcnt vmcnt(2)
	s_nop 0
	v_cndmask_b32_e32 v5, 0, v5, vcc
	v_cndmask_b32_e32 v4, 0, v4, vcc
	v_cndmask_b32_e32 v3, 0, v3, vcc
	v_cndmask_b32_e32 v2, 0, v2, vcc
	v_cmp_lt_i32_e32 vcc, 64, v0
	s_waitcnt vmcnt(1)
	s_nop 0
	v_cndmask_b32_e32 v17, 0, v17, vcc
	v_cndmask_b32_e32 v16, 0, v16, vcc
	v_cndmask_b32_e32 v15, 0, v15, vcc
	v_cndmask_b32_e32 v14, 0, v14, vcc
	v_cmp_lt_i32_e32 vcc, s2, v0
	s_waitcnt vmcnt(0)
	s_nop 0
	v_cndmask_b32_e32 v0, 0, v13, vcc
	v_cndmask_b32_e32 v12, 0, v12, vcc
	v_cndmask_b32_e32 v11, 0, v11, vcc
	v_cndmask_b32_e32 v10, 0, v10, vcc
	s_andn2_b64 vcc, exec, s[22:23]
	ds_write_b16 v134, v6
	ds_write_b16_d16_hi v134, v6 offset:272
	ds_write_b16 v134, v7 offset:544
	ds_write_b16_d16_hi v134, v7 offset:816
	ds_write_b16 v134, v8 offset:1088
	ds_write_b16_d16_hi v134, v8 offset:1360
	ds_write_b16 v134, v9 offset:1632
	ds_write_b16_d16_hi v134, v9 offset:1904
	ds_write_b16 v135, v2
	ds_write_b16_d16_hi v135, v2 offset:272
	ds_write_b16 v135, v3 offset:544
	ds_write_b16_d16_hi v135, v3 offset:816
	ds_write_b16 v135, v4 offset:1088
	ds_write_b16_d16_hi v135, v4 offset:1360
	ds_write_b16 v135, v5 offset:1632
	ds_write_b16_d16_hi v135, v5 offset:1904
	ds_write_b16 v136, v14
	ds_write_b16_d16_hi v136, v14 offset:272
	ds_write_b16 v136, v15 offset:544
	ds_write_b16_d16_hi v136, v15 offset:816
	ds_write_b16 v136, v16 offset:1088
	ds_write_b16_d16_hi v136, v16 offset:1360
	ds_write_b16 v136, v17 offset:1632
	ds_write_b16_d16_hi v136, v17 offset:1904
	ds_write_b16 v137, v10
	ds_write_b16_d16_hi v137, v10 offset:272
	ds_write_b16 v137, v11 offset:544
	ds_write_b16_d16_hi v137, v11 offset:816
	ds_write_b16 v137, v12 offset:1088
	ds_write_b16_d16_hi v137, v12 offset:1360
	ds_write_b16 v137, v0 offset:1632
	ds_write_b16_d16_hi v137, v0 offset:1904
	s_waitcnt lgkmcnt(0)
	s_barrier
	s_cbranch_vccnz .LBB0_925
	v_readlane_b32 s2, v249, 55
	v_readlane_b32 s3, v249, 56
	v_mov_b32_e32 v30, 0
	s_andn2_b64 vcc, exec, s[2:3]
	v_mov_b32_e32 v31, 0
	v_mov_b32_e32 v32, 0
	v_mov_b32_e32 v33, 0
	v_mov_b32_e32 v26, 0
	v_mov_b32_e32 v27, 0
	v_mov_b32_e32 v28, 0
	v_mov_b32_e32 v29, 0
	v_mov_b32_e32 v22, 0
	v_mov_b32_e32 v23, 0
	v_mov_b32_e32 v24, 0
	v_mov_b32_e32 v25, 0
	v_mov_b32_e32 v18, 0
	v_mov_b32_e32 v19, 0
	v_mov_b32_e32 v20, 0
	v_mov_b32_e32 v21, 0
	v_mov_b32_e32 v14, 0
	v_mov_b32_e32 v15, 0
	v_mov_b32_e32 v16, 0
	v_mov_b32_e32 v17, 0
	v_mov_b32_e32 v10, 0
	v_mov_b32_e32 v11, 0
	v_mov_b32_e32 v12, 0
	v_mov_b32_e32 v13, 0
	v_mov_b32_e32 v6, 0
	v_mov_b32_e32 v7, 0
	v_mov_b32_e32 v8, 0
	v_mov_b32_e32 v9, 0
	v_mov_b32_e32 v2, 0
	v_mov_b32_e32 v3, 0
	v_mov_b32_e32 v4, 0
	v_mov_b32_e32 v5, 0
	s_cbranch_vccnz .LBB0_922
	ds_read_b128 v[2:5], v144
	ds_read_b128 v[6:9], v145 offset:4352
	v_readlane_b32 s2, v249, 57
	v_readlane_b32 s3, v249, 58
	s_andn2_b64 vcc, exec, s[2:3]
	s_waitcnt lgkmcnt(1)
	v_mfma_f32_16x16x32_bf16 v[30:33], v[2:5], v[46:49], 0
	ds_read_b128 v[2:5], v146 offset:8704
	ds_read_b128 v[70:73], v151 offset:30464
	s_waitcnt lgkmcnt(2)
	v_mfma_f32_16x16x32_bf16 v[26:29], v[6:9], v[46:49], 0
	ds_read_b128 v[6:9], v147 offset:13056
	s_waitcnt lgkmcnt(2)
	v_mfma_f32_16x16x32_bf16 v[22:25], v[2:5], v[46:49], 0
	ds_read_b128 v[2:5], v148 offset:17408
	s_waitcnt lgkmcnt(1)
	v_mfma_f32_16x16x32_bf16 v[18:21], v[6:9], v[46:49], 0
	ds_read_b128 v[6:9], v149 offset:21760
	s_waitcnt lgkmcnt(1)
	v_mfma_f32_16x16x32_bf16 v[14:17], v[2:5], v[46:49], 0
	ds_read_b128 v[2:5], v150 offset:26112
	s_waitcnt lgkmcnt(1)
	v_mfma_f32_16x16x32_bf16 v[10:13], v[6:9], v[46:49], 0
	s_waitcnt lgkmcnt(0)
	v_mfma_f32_16x16x32_bf16 v[6:9], v[2:5], v[46:49], 0
	v_mfma_f32_16x16x32_bf16 v[2:5], v[70:73], v[46:49], 0
	s_cbranch_vccnz .LBB0_922
; #define LAS __attribute__((address_space(3)))
; __device__ __forceinline__ void mlp_tile(const Ctx& C, int l, int ct, int hd) {
;     ...
; #pragma unroll
;         for (int kk = 0; kk < 4; ++kk) {
;             if (kk >= nk) break;
;             const bf16x8 wf = wfr[kk];
; #pragma unroll
;             for (int n = 0; n < 8; ++n) { const bf16x8 vf = *(const LAS bf16x8*)(VT + (16 * n + fr) * SX + (((4 * kk + fq) ^ (2 * n + (fr >> 3))) << 3));
;                 acc[n] = __builtin_amdgcn_mfma_f32_16x16x32_bf16(vf, wf, acc[n], 0, 0, 0); }
;         }
	ds_read_b128 v[232:235], v152
	ds_read_b128 v[236:239], v153 offset:4352
	ds_read_b128 v[240:243], v154 offset:8704
	ds_read_b128 v[244:247], v155 offset:13056
	v_readlane_b32 s2, v249, 59
	v_readlane_b32 s3, v249, 60
	s_andn2_b64 vcc, exec, s[2:3]
	s_waitcnt lgkmcnt(3)
	v_mfma_f32_16x16x32_bf16 v[30:33], v[232:235], v[42:45], v[30:33]
	ds_read_b128 v[232:235], v156 offset:17408
	s_waitcnt lgkmcnt(3)
	v_mfma_f32_16x16x32_bf16 v[26:29], v[236:239], v[42:45], v[26:29]
	ds_read_b128 v[236:239], v157 offset:21760
	s_waitcnt lgkmcnt(3)
	v_mfma_f32_16x16x32_bf16 v[22:25], v[240:243], v[42:45], v[22:25]
	ds_read_b128 v[240:243], v158 offset:26112
	s_waitcnt lgkmcnt(3)
	v_mfma_f32_16x16x32_bf16 v[18:21], v[244:247], v[42:45], v[18:21]
	ds_read_b128 v[244:247], v159 offset:30464
	s_waitcnt lgkmcnt(3)
	v_mfma_f32_16x16x32_bf16 v[14:17], v[232:235], v[42:45], v[14:17]
	s_waitcnt lgkmcnt(2)
	v_mfma_f32_16x16x32_bf16 v[10:13], v[236:239], v[42:45], v[10:13]
	s_waitcnt lgkmcnt(1)
	v_mfma_f32_16x16x32_bf16 v[6:9], v[240:243], v[42:45], v[6:9]
	s_waitcnt lgkmcnt(0)
	v_mfma_f32_16x16x32_bf16 v[2:5], v[244:247], v[42:45], v[2:5]
	s_cbranch_vccnz .LBB0_922
	ds_read_b128 v[232:235], v160
	ds_read_b128 v[236:239], v161 offset:4352
	ds_read_b128 v[240:243], v162 offset:8704
	ds_read_b128 v[244:247], v163 offset:13056
	v_readlane_b32 s2, v249, 61
	v_readlane_b32 s3, v249, 62
	s_andn2_b64 vcc, exec, s[2:3]
	s_waitcnt lgkmcnt(3)
	v_mfma_f32_16x16x32_bf16 v[30:33], v[232:235], v[38:41], v[30:33]
	ds_read_b128 v[232:235], v164 offset:17408
	s_waitcnt lgkmcnt(3)
	v_mfma_f32_16x16x32_bf16 v[26:29], v[236:239], v[38:41], v[26:29]
	ds_read_b128 v[236:239], v165 offset:21760
	s_waitcnt lgkmcnt(3)
	v_mfma_f32_16x16x32_bf16 v[22:25], v[240:243], v[38:41], v[22:25]
	ds_read_b128 v[240:243], v166 offset:26112
	s_waitcnt lgkmcnt(3)
	v_mfma_f32_16x16x32_bf16 v[18:21], v[244:247], v[38:41], v[18:21]
	ds_read_b128 v[244:247], v167 offset:30464
	s_waitcnt lgkmcnt(3)
	v_mfma_f32_16x16x32_bf16 v[14:17], v[232:235], v[38:41], v[14:17]
	s_waitcnt lgkmcnt(2)
	v_mfma_f32_16x16x32_bf16 v[10:13], v[236:239], v[38:41], v[10:13]
	s_waitcnt lgkmcnt(1)
	v_mfma_f32_16x16x32_bf16 v[6:9], v[240:243], v[38:41], v[6:9]
	s_waitcnt lgkmcnt(0)
	v_mfma_f32_16x16x32_bf16 v[2:5], v[244:247], v[38:41], v[2:5]
	s_cbranch_vccnz .LBB0_922
	ds_read_b128 v[232:235], v168
	ds_read_b128 v[236:239], v169 offset:4352
	ds_read_b128 v[240:243], v170 offset:8704
	ds_read_b128 v[244:247], v171 offset:13056
	s_waitcnt lgkmcnt(3)
	v_mfma_f32_16x16x32_bf16 v[30:33], v[232:235], v[34:37], v[30:33]
	ds_read_b128 v[232:235], v172 offset:17408
	s_waitcnt lgkmcnt(3)
	v_mfma_f32_16x16x32_bf16 v[26:29], v[236:239], v[34:37], v[26:29]
	ds_read_b128 v[236:239], v173 offset:21760
	s_waitcnt lgkmcnt(3)
	v_mfma_f32_16x16x32_bf16 v[22:25], v[240:243], v[34:37], v[22:25]
	ds_read_b128 v[240:243], v174 offset:26112
	s_waitcnt lgkmcnt(3)
	v_mfma_f32_16x16x32_bf16 v[18:21], v[244:247], v[34:37], v[18:21]
	ds_read_b128 v[244:247], v175 offset:30464
	s_waitcnt lgkmcnt(3)
	v_mfma_f32_16x16x32_bf16 v[14:17], v[232:235], v[34:37], v[14:17]
	s_waitcnt lgkmcnt(2)
	v_mfma_f32_16x16x32_bf16 v[10:13], v[236:239], v[34:37], v[10:13]
	s_waitcnt lgkmcnt(1)
	v_mfma_f32_16x16x32_bf16 v[6:9], v[240:243], v[34:37], v[6:9]
	s_waitcnt lgkmcnt(0)
	v_mfma_f32_16x16x32_bf16 v[2:5], v[244:247], v[34:37], v[2:5]
